# FFN2 and WOUT epilogues regenerated with paired dword stores (cvt_pk + DPP exchange + v_perm, 32-bit offsets), on top of FFN1 paired stores
# baseline (speedup 1.0000x reference)
; DI int TIDX() { int t = threadIdx.x; asm volatile("" : "+v"(t)); return t; }
; template <class F>
; DI void epi_foreach(f32x16 (&acc)[2][2], int m0, int n0, F f) {
;   const int lane = TIDX() & 63, w = TIDX() >> 6, wm = w >> 1, wn = w & 1, hh = lane >> 5, c = lane & 31;
; #pragma unroll
;   for (int mi = 0; mi < 2; ++mi)
; #pragma unroll
;     for (int ni = 0; ni < 2; ++ni) f(m0 + wm * 64 + mi * 32 + 4 * hh, n0 + wn * 64 + ni * 32 + c, acc[mi][ni]);
; }
; DI void phase_gemm_plain(const h16* A, int lda, const h16* Bt, int K, h16* C, int ldc, int mt0, int mt1, int ntn, char* smem) {
;     ...
;     epi_foreach(acc, m0, n0, [&](int rbase, int n, const f32x16& v) {
; #pragma unroll
;       for (int i = 0; i < 16; ++i) C[(size_t)EROW(rbase, i) * ldc + n] = (h16)v[i];
;     });
.LBB0_57:
	v_mov_b32_e32 v0, v203
	s_waitcnt vmcnt(0)
	v_mov_b32_e32 v66, v203
	s_barrier
	s_nop 4
	s_nop 7
	v_lshrrev_b32_e32 v67, 3, v203
	v_and_or_b32 v67, v67, 4, s24
	v_lshrrev_b32_e32 v68, 1, v203
	v_and_b32_e32 v68, 0xffffffc0, v68
	v_add_u32_e32 v67, v67, v68
	v_and_b32_e32 v68, 31, v203
	v_and_b32_e32 v69, 64, v203
	v_or3_b32 v68, v68, v69, s23
	v_and_b32_e32 v69, 1, v68
	v_add_u32_e32 v67, v67, v69
	v_and_b32_e32 v68, -2, v68
	v_lshlrev_b32_e32 v68, 1, v68
	v_lshl_add_u32 v66, v67, 11, v68
	v_mov_b32_e32 v70, 0x05040100
	v_mov_b32_e32 v71, 0x03020706
	v_sub_u32_e32 v69, 0, v69
	v_bfi_b32 v70, v69, v71, v70
	v_cvt_pk_f16_f32 v72, v50, v51
	v_cvt_pk_f16_f32 v73, v52, v53
	v_cvt_pk_f16_f32 v74, v54, v55
	v_cvt_pk_f16_f32 v75, v56, v57
	v_mov_b32_e32 v80, v66
	v_add_u32_e32 v81, 0x1000, v66
	v_add_u32_e32 v82, 0x4000, v66
	v_add_u32_e32 v83, 0x5000, v66
	v_mov_b32_dpp v76, v72 quad_perm:[1,0,3,2] row_mask:0xf bank_mask:0xf
	v_mov_b32_dpp v77, v73 quad_perm:[1,0,3,2] row_mask:0xf bank_mask:0xf
	v_mov_b32_dpp v78, v74 quad_perm:[1,0,3,2] row_mask:0xf bank_mask:0xf
	v_mov_b32_dpp v79, v75 quad_perm:[1,0,3,2] row_mask:0xf bank_mask:0xf
	v_perm_b32 v72, v76, v72, v70
	v_perm_b32 v73, v77, v73, v70
	v_perm_b32 v74, v78, v74, v70
	v_perm_b32 v75, v79, v75, v70
	global_store_dword v80, v72, s[6:7]
	global_store_dword v81, v73, s[6:7]
	global_store_dword v82, v74, s[6:7]
	global_store_dword v83, v75, s[6:7]
	v_cvt_pk_f16_f32 v72, v58, v59
	v_cvt_pk_f16_f32 v73, v60, v61
	v_cvt_pk_f16_f32 v74, v62, v63
	v_cvt_pk_f16_f32 v75, v64, v65
	v_add_u32_e32 v80, 0x8000, v66
	v_add_u32_e32 v81, 0x9000, v66
	v_add_u32_e32 v82, 0xc000, v66
	v_add_u32_e32 v83, 0xd000, v66
	v_mov_b32_dpp v76, v72 quad_perm:[1,0,3,2] row_mask:0xf bank_mask:0xf
	v_mov_b32_dpp v77, v73 quad_perm:[1,0,3,2] row_mask:0xf bank_mask:0xf
	v_mov_b32_dpp v78, v74 quad_perm:[1,0,3,2] row_mask:0xf bank_mask:0xf
	v_mov_b32_dpp v79, v75 quad_perm:[1,0,3,2] row_mask:0xf bank_mask:0xf
	v_perm_b32 v72, v76, v72, v70
	v_perm_b32 v73, v77, v73, v70
	v_perm_b32 v74, v78, v74, v70
	v_perm_b32 v75, v79, v75, v70
	global_store_dword v80, v72, s[6:7]
	global_store_dword v81, v73, s[6:7]
	global_store_dword v82, v74, s[6:7]
	global_store_dword v83, v75, s[6:7]
	v_cvt_pk_f16_f32 v72, v34, v35
	v_cvt_pk_f16_f32 v73, v36, v37
	v_cvt_pk_f16_f32 v74, v38, v39
	v_cvt_pk_f16_f32 v75, v40, v41
	v_add_u32_e32 v80, 0x40, v66
	v_add_u32_e32 v81, 0x1040, v66
	v_add_u32_e32 v82, 0x4040, v66
	v_add_u32_e32 v83, 0x5040, v66
	v_mov_b32_dpp v76, v72 quad_perm:[1,0,3,2] row_mask:0xf bank_mask:0xf
	v_mov_b32_dpp v77, v73 quad_perm:[1,0,3,2] row_mask:0xf bank_mask:0xf
	v_mov_b32_dpp v78, v74 quad_perm:[1,0,3,2] row_mask:0xf bank_mask:0xf
	v_mov_b32_dpp v79, v75 quad_perm:[1,0,3,2] row_mask:0xf bank_mask:0xf
	v_perm_b32 v72, v76, v72, v70
	v_perm_b32 v73, v77, v73, v70
	v_perm_b32 v74, v78, v74, v70
	v_perm_b32 v75, v79, v75, v70
	global_store_dword v80, v72, s[6:7]
	global_store_dword v81, v73, s[6:7]
	global_store_dword v82, v74, s[6:7]
	global_store_dword v83, v75, s[6:7]
	v_cvt_pk_f16_f32 v72, v42, v43
	v_cvt_pk_f16_f32 v73, v44, v45
	v_cvt_pk_f16_f32 v74, v46, v47
	v_cvt_pk_f16_f32 v75, v48, v49
	v_add_u32_e32 v80, 0x8040, v66
	v_add_u32_e32 v81, 0x9040, v66
	v_add_u32_e32 v82, 0xc040, v66
	v_add_u32_e32 v83, 0xd040, v66
	v_mov_b32_dpp v76, v72 quad_perm:[1,0,3,2] row_mask:0xf bank_mask:0xf
	v_mov_b32_dpp v77, v73 quad_perm:[1,0,3,2] row_mask:0xf bank_mask:0xf
	v_mov_b32_dpp v78, v74 quad_perm:[1,0,3,2] row_mask:0xf bank_mask:0xf
	v_mov_b32_dpp v79, v75 quad_perm:[1,0,3,2] row_mask:0xf bank_mask:0xf
	v_perm_b32 v72, v76, v72, v70
; DI int TIDX() { int t = threadIdx.x; asm volatile("" : "+v"(t)); return t; }
; template <class F>
; DI void epi_foreach(f32x16 (&acc)[2][2], int m0, int n0, F f) {
;   const int lane = TIDX() & 63, w = TIDX() >> 6, wm = w >> 1, wn = w & 1, hh = lane >> 5, c = lane & 31;
; #pragma unroll
;   for (int mi = 0; mi < 2; ++mi)
; #pragma unroll
;     for (int ni = 0; ni < 2; ++ni) f(m0 + wm * 64 + mi * 32 + 4 * hh, n0 + wn * 64 + ni * 32 + c, acc[mi][ni]);
; }
; DI void phase_gemm_plain(const h16* A, int lda, const h16* Bt, int K, h16* C, int ldc, int mt0, int mt1, int ntn, char* smem) {
;     ...
;     epi_foreach(acc, m0, n0, [&](int rbase, int n, const f32x16& v) {
; #pragma unroll
;       for (int i = 0; i < 16; ++i) C[(size_t)EROW(rbase, i) * ldc + n] = (h16)v[i];
;     });
	v_perm_b32 v73, v77, v73, v70
	v_perm_b32 v74, v78, v74, v70
	v_perm_b32 v75, v79, v75, v70
	global_store_dword v80, v72, s[6:7]
	global_store_dword v81, v73, s[6:7]
	global_store_dword v82, v74, s[6:7]
	global_store_dword v83, v75, s[6:7]
	v_cvt_pk_f16_f32 v72, v18, v19
	v_cvt_pk_f16_f32 v73, v20, v21
	v_cvt_pk_f16_f32 v74, v22, v23
	v_cvt_pk_f16_f32 v75, v24, v25
	v_add_u32_e32 v80, 0x10000, v66
	v_add_u32_e32 v81, 0x11000, v66
	v_add_u32_e32 v82, 0x14000, v66
	v_add_u32_e32 v83, 0x15000, v66
	v_mov_b32_dpp v76, v72 quad_perm:[1,0,3,2] row_mask:0xf bank_mask:0xf
	v_mov_b32_dpp v77, v73 quad_perm:[1,0,3,2] row_mask:0xf bank_mask:0xf
	v_mov_b32_dpp v78, v74 quad_perm:[1,0,3,2] row_mask:0xf bank_mask:0xf
	v_mov_b32_dpp v79, v75 quad_perm:[1,0,3,2] row_mask:0xf bank_mask:0xf
	v_perm_b32 v72, v76, v72, v70
	v_perm_b32 v73, v77, v73, v70
	v_perm_b32 v74, v78, v74, v70
	v_perm_b32 v75, v79, v75, v70
	global_store_dword v80, v72, s[6:7]
	global_store_dword v81, v73, s[6:7]
	global_store_dword v82, v74, s[6:7]
	global_store_dword v83, v75, s[6:7]
	v_cvt_pk_f16_f32 v72, v26, v27
	v_cvt_pk_f16_f32 v73, v28, v29
	v_cvt_pk_f16_f32 v74, v30, v31
	v_cvt_pk_f16_f32 v75, v32, v33
	v_add_u32_e32 v80, 0x18000, v66
	v_add_u32_e32 v81, 0x19000, v66
	v_add_u32_e32 v82, 0x1c000, v66
	v_add_u32_e32 v83, 0x1d000, v66
	v_mov_b32_dpp v76, v72 quad_perm:[1,0,3,2] row_mask:0xf bank_mask:0xf
	v_mov_b32_dpp v77, v73 quad_perm:[1,0,3,2] row_mask:0xf bank_mask:0xf
	v_mov_b32_dpp v78, v74 quad_perm:[1,0,3,2] row_mask:0xf bank_mask:0xf
	v_mov_b32_dpp v79, v75 quad_perm:[1,0,3,2] row_mask:0xf bank_mask:0xf
	v_perm_b32 v72, v76, v72, v70
	v_perm_b32 v73, v77, v73, v70
	v_perm_b32 v74, v78, v74, v70
	v_perm_b32 v75, v79, v75, v70
	global_store_dword v80, v72, s[6:7]
	global_store_dword v81, v73, s[6:7]
	global_store_dword v82, v74, s[6:7]
	global_store_dword v83, v75, s[6:7]
	v_cvt_pk_f16_f32 v72, v2, v3
	v_cvt_pk_f16_f32 v73, v4, v5
	v_cvt_pk_f16_f32 v74, v6, v7
	v_cvt_pk_f16_f32 v75, v8, v9
	v_add_u32_e32 v80, 0x10040, v66
	v_add_u32_e32 v81, 0x11040, v66
	v_add_u32_e32 v82, 0x14040, v66
	v_add_u32_e32 v83, 0x15040, v66
	v_mov_b32_dpp v76, v72 quad_perm:[1,0,3,2] row_mask:0xf bank_mask:0xf
	v_mov_b32_dpp v77, v73 quad_perm:[1,0,3,2] row_mask:0xf bank_mask:0xf
	v_mov_b32_dpp v78, v74 quad_perm:[1,0,3,2] row_mask:0xf bank_mask:0xf
	v_mov_b32_dpp v79, v75 quad_perm:[1,0,3,2] row_mask:0xf bank_mask:0xf
	v_perm_b32 v72, v76, v72, v70
	v_perm_b32 v73, v77, v73, v70
	v_perm_b32 v74, v78, v74, v70
	v_perm_b32 v75, v79, v75, v70
	global_store_dword v80, v72, s[6:7]
	global_store_dword v81, v73, s[6:7]
	global_store_dword v82, v74, s[6:7]
	global_store_dword v83, v75, s[6:7]
	v_cvt_pk_f16_f32 v72, v10, v11
	v_cvt_pk_f16_f32 v73, v12, v13
	v_cvt_pk_f16_f32 v74, v14, v15
	v_cvt_pk_f16_f32 v75, v16, v17
	v_add_u32_e32 v80, 0x18040, v66
	v_add_u32_e32 v81, 0x19040, v66
	v_add_u32_e32 v82, 0x1c040, v66
	v_add_u32_e32 v83, 0x1d040, v66
	v_mov_b32_dpp v76, v72 quad_perm:[1,0,3,2] row_mask:0xf bank_mask:0xf
	v_mov_b32_dpp v77, v73 quad_perm:[1,0,3,2] row_mask:0xf bank_mask:0xf
	v_mov_b32_dpp v78, v74 quad_perm:[1,0,3,2] row_mask:0xf bank_mask:0xf
	v_mov_b32_dpp v79, v75 quad_perm:[1,0,3,2] row_mask:0xf bank_mask:0xf
	v_perm_b32 v72, v76, v72, v70
	v_perm_b32 v73, v77, v73, v70
	v_perm_b32 v74, v78, v74, v70
	v_perm_b32 v75, v79, v75, v70
	global_store_dword v80, v72, s[6:7]
	global_store_dword v81, v73, s[6:7]
	global_store_dword v82, v74, s[6:7]
	global_store_dword v83, v75, s[6:7]
	v_readlane_b32 s2, v252, 63
	s_add_i32 s15, s15, s2
	s_cmp_ge_i32 s15, s14
	s_cbranch_scc1 .LBB0_64

; DI int TIDX() { int t = threadIdx.x; asm volatile("" : "+v"(t)); return t; }
; template <class F>
; DI void epi_foreach(f32x16 (&acc)[2][2], int m0, int n0, F f) {
;   const int lane = TIDX() & 63, w = TIDX() >> 6, wm = w >> 1, wn = w & 1, hh = lane >> 5, c = lane & 31;
; #pragma unroll
;   for (int mi = 0; mi < 2; ++mi)
; #pragma unroll
;     for (int ni = 0; ni < 2; ++ni) f(m0 + wm * 64 + mi * 32 + 4 * hh, n0 + wn * 64 + ni * 32 + c, acc[mi][ni]);
; }
; DI void phase_gemm_plain(const h16* A, int lda, const h16* Bt, int K, h16* C, int ldc, int mt0, int mt1, int ntn, char* smem) {
;     ...
;     epi_foreach(acc, m0, n0, [&](int rbase, int n, const f32x16& v) {
; #pragma unroll
;       for (int i = 0; i < 16; ++i) C[(size_t)EROW(rbase, i) * ldc + n] = (h16)v[i];
;     });
.LBB0_90:
	v_mov_b32_e32 v0, v203
	s_waitcnt vmcnt(0)
	v_mov_b32_e32 v66, v203
	s_barrier
	s_nop 4
	s_nop 7
	v_lshrrev_b32_e32 v67, 3, v203
	v_and_or_b32 v67, v67, 4, s6
	v_lshrrev_b32_e32 v68, 1, v203
	v_and_b32_e32 v68, 0xffffffc0, v68
	v_add_u32_e32 v67, v67, v68
	v_and_b32_e32 v68, 31, v203
	v_and_b32_e32 v69, 64, v203
	v_or3_b32 v68, v68, v69, s4
	v_and_b32_e32 v69, 1, v68
	v_add_u32_e32 v67, v67, v69
	v_and_b32_e32 v68, -2, v68
	v_lshlrev_b32_e32 v68, 1, v68
	v_lshl_add_u32 v66, v67, 11, v68
	v_mov_b32_e32 v70, 0x05040100
	v_mov_b32_e32 v71, 0x03020706
	v_sub_u32_e32 v69, 0, v69
	v_bfi_b32 v70, v69, v71, v70
	v_cvt_pk_f16_f32 v72, v50, v51
	v_cvt_pk_f16_f32 v73, v52, v53
	v_cvt_pk_f16_f32 v74, v54, v55
	v_cvt_pk_f16_f32 v75, v56, v57
	v_mov_b32_e32 v80, v66
	v_add_u32_e32 v81, 0x1000, v66
	v_add_u32_e32 v82, 0x4000, v66
	v_add_u32_e32 v83, 0x5000, v66
	v_mov_b32_dpp v76, v72 quad_perm:[1,0,3,2] row_mask:0xf bank_mask:0xf
	v_mov_b32_dpp v77, v73 quad_perm:[1,0,3,2] row_mask:0xf bank_mask:0xf
	v_mov_b32_dpp v78, v74 quad_perm:[1,0,3,2] row_mask:0xf bank_mask:0xf
	v_mov_b32_dpp v79, v75 quad_perm:[1,0,3,2] row_mask:0xf bank_mask:0xf
	v_perm_b32 v72, v76, v72, v70
	v_perm_b32 v73, v77, v73, v70
	v_perm_b32 v74, v78, v74, v70
	v_perm_b32 v75, v79, v75, v70
	global_store_dword v80, v72, s[0:1]
	global_store_dword v81, v73, s[0:1]
	global_store_dword v82, v74, s[0:1]
	global_store_dword v83, v75, s[0:1]
	v_cvt_pk_f16_f32 v72, v58, v59
	v_cvt_pk_f16_f32 v73, v60, v61
	v_cvt_pk_f16_f32 v74, v62, v63
	v_cvt_pk_f16_f32 v75, v64, v65
	v_add_u32_e32 v80, 0x8000, v66
	v_add_u32_e32 v81, 0x9000, v66
	v_add_u32_e32 v82, 0xc000, v66
	v_add_u32_e32 v83, 0xd000, v66
	v_mov_b32_dpp v76, v72 quad_perm:[1,0,3,2] row_mask:0xf bank_mask:0xf
	v_mov_b32_dpp v77, v73 quad_perm:[1,0,3,2] row_mask:0xf bank_mask:0xf
	v_mov_b32_dpp v78, v74 quad_perm:[1,0,3,2] row_mask:0xf bank_mask:0xf
	v_mov_b32_dpp v79, v75 quad_perm:[1,0,3,2] row_mask:0xf bank_mask:0xf
	v_perm_b32 v72, v76, v72, v70
	v_perm_b32 v73, v77, v73, v70
	v_perm_b32 v74, v78, v74, v70
	v_perm_b32 v75, v79, v75, v70
	global_store_dword v80, v72, s[0:1]
	global_store_dword v81, v73, s[0:1]
	global_store_dword v82, v74, s[0:1]
	global_store_dword v83, v75, s[0:1]
	v_cvt_pk_f16_f32 v72, v34, v35
	v_cvt_pk_f16_f32 v73, v36, v37
	v_cvt_pk_f16_f32 v74, v38, v39
	v_cvt_pk_f16_f32 v75, v40, v41
	v_add_u32_e32 v80, 0x40, v66
	v_add_u32_e32 v81, 0x1040, v66
	v_add_u32_e32 v82, 0x4040, v66
	v_add_u32_e32 v83, 0x5040, v66
	v_mov_b32_dpp v76, v72 quad_perm:[1,0,3,2] row_mask:0xf bank_mask:0xf
	v_mov_b32_dpp v77, v73 quad_perm:[1,0,3,2] row_mask:0xf bank_mask:0xf
	v_mov_b32_dpp v78, v74 quad_perm:[1,0,3,2] row_mask:0xf bank_mask:0xf
	v_mov_b32_dpp v79, v75 quad_perm:[1,0,3,2] row_mask:0xf bank_mask:0xf
	v_perm_b32 v72, v76, v72, v70
	v_perm_b32 v73, v77, v73, v70
	v_perm_b32 v74, v78, v74, v70
	v_perm_b32 v75, v79, v75, v70
	global_store_dword v80, v72, s[0:1]
	global_store_dword v81, v73, s[0:1]
	global_store_dword v82, v74, s[0:1]
	global_store_dword v83, v75, s[0:1]
	v_cvt_pk_f16_f32 v72, v42, v43
	v_cvt_pk_f16_f32 v73, v44, v45
	v_cvt_pk_f16_f32 v74, v46, v47
	v_cvt_pk_f16_f32 v75, v48, v49
	v_add_u32_e32 v80, 0x8040, v66
	v_add_u32_e32 v81, 0x9040, v66
	v_add_u32_e32 v82, 0xc040, v66
	v_add_u32_e32 v83, 0xd040, v66
	v_mov_b32_dpp v76, v72 quad_perm:[1,0,3,2] row_mask:0xf bank_mask:0xf
	v_mov_b32_dpp v77, v73 quad_perm:[1,0,3,2] row_mask:0xf bank_mask:0xf
	v_mov_b32_dpp v78, v74 quad_perm:[1,0,3,2] row_mask:0xf bank_mask:0xf
	v_mov_b32_dpp v79, v75 quad_perm:[1,0,3,2] row_mask:0xf bank_mask:0xf
	v_perm_b32 v72, v76, v72, v70
; DI int TIDX() { int t = threadIdx.x; asm volatile("" : "+v"(t)); return t; }
; template <class F>
; DI void epi_foreach(f32x16 (&acc)[2][2], int m0, int n0, F f) {
;   const int lane = TIDX() & 63, w = TIDX() >> 6, wm = w >> 1, wn = w & 1, hh = lane >> 5, c = lane & 31;
; #pragma unroll
;   for (int mi = 0; mi < 2; ++mi)
; #pragma unroll
;     for (int ni = 0; ni < 2; ++ni) f(m0 + wm * 64 + mi * 32 + 4 * hh, n0 + wn * 64 + ni * 32 + c, acc[mi][ni]);
; }
; DI void phase_gemm_plain(const h16* A, int lda, const h16* Bt, int K, h16* C, int ldc, int mt0, int mt1, int ntn, char* smem) {
;     ...
;     epi_foreach(acc, m0, n0, [&](int rbase, int n, const f32x16& v) {
; #pragma unroll
;       for (int i = 0; i < 16; ++i) C[(size_t)EROW(rbase, i) * ldc + n] = (h16)v[i];
;     });
	v_perm_b32 v73, v77, v73, v70
	v_perm_b32 v74, v78, v74, v70
	v_perm_b32 v75, v79, v75, v70
	global_store_dword v80, v72, s[0:1]
	global_store_dword v81, v73, s[0:1]
	global_store_dword v82, v74, s[0:1]
	global_store_dword v83, v75, s[0:1]
	v_cvt_pk_f16_f32 v72, v18, v19
	v_cvt_pk_f16_f32 v73, v20, v21
	v_cvt_pk_f16_f32 v74, v22, v23
	v_cvt_pk_f16_f32 v75, v24, v25
	v_add_u32_e32 v80, 0x10000, v66
	v_add_u32_e32 v81, 0x11000, v66
	v_add_u32_e32 v82, 0x14000, v66
	v_add_u32_e32 v83, 0x15000, v66
	v_mov_b32_dpp v76, v72 quad_perm:[1,0,3,2] row_mask:0xf bank_mask:0xf
	v_mov_b32_dpp v77, v73 quad_perm:[1,0,3,2] row_mask:0xf bank_mask:0xf
	v_mov_b32_dpp v78, v74 quad_perm:[1,0,3,2] row_mask:0xf bank_mask:0xf
	v_mov_b32_dpp v79, v75 quad_perm:[1,0,3,2] row_mask:0xf bank_mask:0xf
	v_perm_b32 v72, v76, v72, v70
	v_perm_b32 v73, v77, v73, v70
	v_perm_b32 v74, v78, v74, v70
	v_perm_b32 v75, v79, v75, v70
	global_store_dword v80, v72, s[0:1]
	global_store_dword v81, v73, s[0:1]
	global_store_dword v82, v74, s[0:1]
	global_store_dword v83, v75, s[0:1]
	v_cvt_pk_f16_f32 v72, v26, v27
	v_cvt_pk_f16_f32 v73, v28, v29
	v_cvt_pk_f16_f32 v74, v30, v31
	v_cvt_pk_f16_f32 v75, v32, v33
	v_add_u32_e32 v80, 0x18000, v66
	v_add_u32_e32 v81, 0x19000, v66
	v_add_u32_e32 v82, 0x1c000, v66
	v_add_u32_e32 v83, 0x1d000, v66
	v_mov_b32_dpp v76, v72 quad_perm:[1,0,3,2] row_mask:0xf bank_mask:0xf
	v_mov_b32_dpp v77, v73 quad_perm:[1,0,3,2] row_mask:0xf bank_mask:0xf
	v_mov_b32_dpp v78, v74 quad_perm:[1,0,3,2] row_mask:0xf bank_mask:0xf
	v_mov_b32_dpp v79, v75 quad_perm:[1,0,3,2] row_mask:0xf bank_mask:0xf
	v_perm_b32 v72, v76, v72, v70
	v_perm_b32 v73, v77, v73, v70
	v_perm_b32 v74, v78, v74, v70
	v_perm_b32 v75, v79, v75, v70
	global_store_dword v80, v72, s[0:1]
	global_store_dword v81, v73, s[0:1]
	global_store_dword v82, v74, s[0:1]
	global_store_dword v83, v75, s[0:1]
	v_cvt_pk_f16_f32 v72, v2, v3
	v_cvt_pk_f16_f32 v73, v4, v5
	v_cvt_pk_f16_f32 v74, v6, v7
	v_cvt_pk_f16_f32 v75, v8, v9
	v_add_u32_e32 v80, 0x10040, v66
	v_add_u32_e32 v81, 0x11040, v66
	v_add_u32_e32 v82, 0x14040, v66
	v_add_u32_e32 v83, 0x15040, v66
	v_mov_b32_dpp v76, v72 quad_perm:[1,0,3,2] row_mask:0xf bank_mask:0xf
	v_mov_b32_dpp v77, v73 quad_perm:[1,0,3,2] row_mask:0xf bank_mask:0xf
	v_mov_b32_dpp v78, v74 quad_perm:[1,0,3,2] row_mask:0xf bank_mask:0xf
	v_mov_b32_dpp v79, v75 quad_perm:[1,0,3,2] row_mask:0xf bank_mask:0xf
	v_perm_b32 v72, v76, v72, v70
	v_perm_b32 v73, v77, v73, v70
	v_perm_b32 v74, v78, v74, v70
	v_perm_b32 v75, v79, v75, v70
	global_store_dword v80, v72, s[0:1]
	global_store_dword v81, v73, s[0:1]
	global_store_dword v82, v74, s[0:1]
	global_store_dword v83, v75, s[0:1]
	v_cvt_pk_f16_f32 v72, v10, v11
	v_cvt_pk_f16_f32 v73, v12, v13
	v_cvt_pk_f16_f32 v74, v14, v15
	v_cvt_pk_f16_f32 v75, v16, v17
	v_add_u32_e32 v80, 0x18040, v66
	v_add_u32_e32 v81, 0x19040, v66
	v_add_u32_e32 v82, 0x1c040, v66
	v_add_u32_e32 v83, 0x1d040, v66
	v_mov_b32_dpp v76, v72 quad_perm:[1,0,3,2] row_mask:0xf bank_mask:0xf
	v_mov_b32_dpp v77, v73 quad_perm:[1,0,3,2] row_mask:0xf bank_mask:0xf
	v_mov_b32_dpp v78, v74 quad_perm:[1,0,3,2] row_mask:0xf bank_mask:0xf
	v_mov_b32_dpp v79, v75 quad_perm:[1,0,3,2] row_mask:0xf bank_mask:0xf
	v_perm_b32 v72, v76, v72, v70
	v_perm_b32 v73, v77, v73, v70
	v_perm_b32 v74, v78, v74, v70
	v_perm_b32 v75, v79, v75, v70
	global_store_dword v80, v72, s[0:1]
	global_store_dword v81, v73, s[0:1]
	global_store_dword v82, v74, s[0:1]
	global_store_dword v83, v75, s[0:1]
	v_readlane_b32 s2, v252, 63
	s_add_i32 s15, s15, s2
	s_cmp_ge_i32 s15, s14
	s_cbranch_scc1 .LBB0_97
